# p1_scan LDS layout padded by 16B per 8 threads (removes 64-way bank conflict in the cross-thread prefix phase)
# baseline (speedup 1.0000x reference)
.Lstag_done:
	s_add_u32 s48, s70, 0x200000
	s_addc_u32 s49, s71, 0
	v_readlane_b32 s0, v245, 2
	s_cmp_gt_i32 s0, 15
	s_waitcnt lgkmcnt(0)
	s_barrier
	s_cbranch_scc1 .LBB0_167
	v_mov_b32_e32 v2, v0
	s_lshl_b32 s0, s75, 1
	v_mbcnt_lo_u32_b32 v104, -1, 0
	v_mbcnt_hi_u32_b32 v104, -1, v104
	s_add_i32 s0, s0, s80
	v_readfirstlane_b32 s4, v2
	s_and_b32 s1, s4, 0xffffffc0
	v_add_u32_e32 v20, s1, v104
	s_ashr_i32 s1, s0, 31
	v_lshlrev_b32_e32 v42, 2, v20
	s_lshl_b64 s[2:3], s[0:1], 16
	v_ashrrev_i32_e32 v43, 31, v42
	s_add_u32 s2, s18, s2
	s_addc_u32 s3, s19, s3
	v_lshlrev_b64 v[2:3], 5, v[42:43]
	v_lshl_add_u64 v[18:19], s[2:3], 0, v[2:3]
	global_load_dwordx4 v[2:5], v[18:19], off
	global_load_dwordx4 v[6:9], v[18:19], off offset:32
	global_load_dwordx4 v[10:13], v[18:19], off offset:64
	global_load_dwordx4 v[14:17], v[18:19], off offset:96
	global_load_dwordx4 v[68:71], v[18:19], off offset:16
	global_load_dwordx4 v[72:75], v[18:19], off offset:48
	global_load_dwordx4 v[76:79], v[18:19], off offset:80
	global_load_dwordx4 v[80:83], v[18:19], off offset:112
	s_lshr_b32 s1, s4, 3
	v_lshl_add_u32 v105, v20, 6, 0
	v_lshrrev_b32_e32 v107, 3, v20
	v_lshl_add_u32 v105, v107, 4, v105
	s_and_b32 s1, s1, 0x1ffffff8
	s_add_i32 s1, s1, 0
	v_lshl_add_u32 v106, v104, 9, s1
	v_lshl_add_u32 v106, v104, 4, v106
	v_mbcnt_hi_u32_b32 v107, -1, v1
	v_and_b32_e32 v108, 64, v107
	s_waitcnt vmcnt(8)
	v_add_u32_e32 v100, -1, v107
	v_cmp_lt_i32_e32 vcc, v100, v108
	v_add_u32_e32 v102, -2, v107
	s_lshl_b32 s0, s0, 3
	v_cndmask_b32_e32 v100, v100, v107, vcc
	v_lshlrev_b32_e32 v101, 2, v100
	v_cmp_gt_i32_e32 vcc, 1, v104
	s_ashr_i32 s1, s0, 31
	s_mov_b32 s2, 0x652b82fe
	s_lshl_b64 s[4:5], s[0:1], 13
	s_mov_b32 s3, 0xbff71547
	s_add_u32 s4, s48, s4
	s_addc_u32 s5, s49, s5
	s_waitcnt vmcnt(7)
	v_cvt_f64_f32_e32 v[66:67], v2
	v_cvt_f64_f32_e32 v[58:59], v3
	v_cvt_f64_f32_e32 v[50:51], v4
	v_cvt_f64_f32_e32 v[40:41], v5
	s_waitcnt vmcnt(6)
	v_cvt_f64_f32_e32 v[64:65], v6
	s_waitcnt vmcnt(4)
	v_cvt_f64_f32_e32 v[60:61], v14
	v_cvt_f64_f32_e32 v[56:57], v7
	v_cvt_f64_f32_e32 v[52:53], v15
	v_cvt_f64_f32_e32 v[48:49], v8
	v_cvt_f64_f32_e32 v[44:45], v16
	v_cvt_f64_f32_e32 v[38:39], v9
	v_cvt_f64_f32_e32 v[34:35], v17
	s_waitcnt vmcnt(3)
	v_cvt_f64_f32_e32 v[32:33], v68
	s_waitcnt vmcnt(2)
	v_cvt_f64_f32_e32 v[30:31], v72
	v_cvt_f64_f32_e32 v[24:25], v69
	v_cvt_f64_f32_e32 v[22:23], v73
	v_cvt_f64_f32_e32 v[16:17], v70
	v_cvt_f64_f32_e32 v[14:15], v74
	v_cvt_f64_f32_e32 v[8:9], v71
	v_cvt_f64_f32_e32 v[6:7], v75
	v_add_f64 v[68:69], v[66:67], 0
	v_add_f64 v[70:71], v[58:59], 0
	v_add_f64 v[72:73], v[50:51], 0
	v_add_f64 v[74:75], v[40:41], 0
	v_cvt_f64_f32_e32 v[62:63], v10
	v_cvt_f64_f32_e32 v[54:55], v11
	v_cvt_f64_f32_e32 v[46:47], v12
	v_cvt_f64_f32_e32 v[36:37], v13
	s_waitcnt vmcnt(1)
	v_cvt_f64_f32_e32 v[28:29], v76
	s_waitcnt vmcnt(0)
	v_cvt_f64_f32_e32 v[26:27], v80
	v_cvt_f64_f32_e32 v[20:21], v77
	v_cvt_f64_f32_e32 v[18:19], v81
	v_cvt_f64_f32_e32 v[12:13], v78
	v_cvt_f64_f32_e32 v[10:11], v82
	v_cvt_f64_f32_e32 v[4:5], v79
	v_cvt_f64_f32_e32 v[2:3], v83
	v_add_f64 v[76:77], v[32:33], 0
	v_add_f64 v[78:79], v[24:25], 0
	v_add_f64 v[80:81], v[16:17], 0
	v_add_f64 v[82:83], v[8:9], 0
	v_add_f64 v[68:69], v[68:69], v[64:65]
	v_add_f64 v[70:71], v[70:71], v[56:57]
	v_add_f64 v[72:73], v[72:73], v[48:49]
	v_add_f64 v[74:75], v[74:75], v[38:39]
	v_add_f64 v[76:77], v[76:77], v[30:31]
	v_add_f64 v[78:79], v[78:79], v[22:23]
	v_add_f64 v[80:81], v[80:81], v[14:15]
	v_add_f64 v[82:83], v[82:83], v[6:7]
	v_add_f64 v[68:69], v[68:69], v[62:63]
	v_add_f64 v[70:71], v[70:71], v[54:55]
	v_add_f64 v[72:73], v[72:73], v[46:47]
	v_add_f64 v[74:75], v[74:75], v[36:37]
	v_add_f64 v[76:77], v[76:77], v[28:29]
	v_add_f64 v[78:79], v[78:79], v[20:21]
	v_add_f64 v[80:81], v[80:81], v[12:13]
	v_add_f64 v[82:83], v[82:83], v[4:5]
	v_add_f64 v[68:69], v[68:69], v[60:61]
	v_add_f64 v[70:71], v[70:71], v[52:53]
	v_add_f64 v[72:73], v[72:73], v[44:45]
	v_add_f64 v[74:75], v[74:75], v[34:35]
	v_add_f64 v[76:77], v[76:77], v[26:27]
	v_add_f64 v[78:79], v[78:79], v[18:19]
	v_add_f64 v[80:81], v[80:81], v[10:11]
	v_add_f64 v[82:83], v[82:83], v[2:3]
	ds_write_b128 v105, v[68:71]
	ds_write_b128 v105, v[72:75] offset:16
	ds_write_b128 v105, v[76:79] offset:32
	ds_write_b128 v105, v[80:83] offset:48
	s_waitcnt lgkmcnt(0)
	s_barrier
	ds_read2_b64 v[68:71], v106 offset1:8
	ds_read2_b64 v[72:75], v106 offset0:16 offset1:24
	ds_read2_b64 v[76:79], v106 offset0:32 offset1:40
	ds_read2_b64 v[80:83], v106 offset0:48 offset1:56
	s_waitcnt lgkmcnt(3)
	v_add_f64 v[84:85], v[68:69], 0
	v_add_f64 v[86:87], v[84:85], v[70:71]
	s_waitcnt lgkmcnt(2)
	v_add_f64 v[88:89], v[86:87], v[72:73]
	v_add_f64 v[90:91], v[88:89], v[74:75]
	s_waitcnt lgkmcnt(1)
	v_add_f64 v[92:93], v[90:91], v[76:77]
	v_add_f64 v[94:95], v[92:93], v[78:79]
	s_waitcnt lgkmcnt(0)
	v_add_f64 v[96:97], v[94:95], v[80:81]
	v_add_f64 v[98:99], v[96:97], v[82:83]
	ds_bpermute_b32 v100, v101, v98
	ds_bpermute_b32 v101, v101, v99
	s_waitcnt lgkmcnt(0)
	v_add_f64 v[100:101], v[98:99], v[100:101]
	v_cndmask_b32_e32 v101, v101, v99, vcc
	v_cndmask_b32_e32 v100, v100, v98, vcc
	v_cmp_lt_i32_e32 vcc, v102, v108
	s_nop 1
	v_cndmask_b32_e32 v102, v102, v107, vcc
	v_lshlrev_b32_e32 v103, 2, v102
	ds_bpermute_b32 v102, v103, v100
	ds_bpermute_b32 v103, v103, v101
	v_cmp_gt_i32_e32 vcc, 2, v104
	s_waitcnt lgkmcnt(0)
	v_add_f64 v[102:103], v[100:101], v[102:103]
	v_cndmask_b32_e32 v100, v102, v100, vcc
	v_add_u32_e32 v102, -4, v107
	v_cndmask_b32_e32 v101, v103, v101, vcc
	v_cmp_lt_i32_e32 vcc, v102, v108
	s_nop 1
	v_cndmask_b32_e32 v102, v102, v107, vcc
	v_lshlrev_b32_e32 v103, 2, v102
	ds_bpermute_b32 v102, v103, v100
	ds_bpermute_b32 v103, v103, v101
	v_cmp_gt_i32_e32 vcc, 4, v104
	s_waitcnt lgkmcnt(0)
	v_add_f64 v[102:103], v[100:101], v[102:103]
	v_cndmask_b32_e32 v100, v102, v100, vcc
	v_add_u32_e32 v102, -8, v107
	v_cndmask_b32_e32 v101, v103, v101, vcc
	v_cmp_lt_i32_e32 vcc, v102, v108
	s_nop 1
	v_cndmask_b32_e32 v102, v102, v107, vcc
	v_lshlrev_b32_e32 v103, 2, v102
	ds_bpermute_b32 v102, v103, v100
	ds_bpermute_b32 v103, v103, v101
	v_cmp_gt_i32_e32 vcc, 8, v104
	s_waitcnt lgkmcnt(0)
	v_add_f64 v[102:103], v[100:101], v[102:103]
	v_cndmask_b32_e32 v100, v102, v100, vcc
	v_add_u32_e32 v102, -16, v107
	v_cndmask_b32_e32 v101, v103, v101, vcc
	v_cmp_lt_i32_e32 vcc, v102, v108
	s_nop 1
	v_cndmask_b32_e32 v102, v102, v107, vcc
	v_lshlrev_b32_e32 v103, 2, v102
	ds_bpermute_b32 v102, v103, v100
	ds_bpermute_b32 v103, v103, v101
	v_cmp_gt_i32_e32 vcc, 16, v104
	s_waitcnt lgkmcnt(0)
	v_add_f64 v[102:103], v[100:101], v[102:103]
	v_cndmask_b32_e32 v100, v102, v100, vcc
	v_subrev_u32_e32 v102, 32, v107
	v_cndmask_b32_e32 v101, v103, v101, vcc
	v_cmp_lt_i32_e32 vcc, v102, v108
	s_nop 1
	v_cndmask_b32_e32 v102, v102, v107, vcc
	v_lshlrev_b32_e32 v103, 2, v102
	ds_bpermute_b32 v102, v103, v100
	ds_bpermute_b32 v103, v103, v101
	v_cmp_gt_i32_e32 vcc, 32, v104
	s_waitcnt lgkmcnt(0)
	v_add_f64 v[102:103], v[100:101], v[102:103]
	v_cndmask_b32_e32 v101, v103, v101, vcc
	v_cndmask_b32_e32 v100, v102, v100, vcc
	v_add_f64 v[100:101], v[100:101], -v[98:99]
	v_add_f64 v[84:85], v[84:85], v[100:101]
	v_add_f64 v[68:69], v[84:85], -v[68:69]
	v_add_f64 v[84:85], v[86:87], v[100:101]
	v_add_f64 v[70:71], v[84:85], -v[70:71]
	ds_write2_b64 v106, v[68:69], v[70:71] offset1:8
	v_add_f64 v[68:69], v[88:89], v[100:101]
	v_add_f64 v[70:71], v[90:91], v[100:101]
	v_add_f64 v[68:69], v[68:69], -v[72:73]
	v_add_f64 v[70:71], v[70:71], -v[74:75]
	ds_write2_b64 v106, v[68:69], v[70:71] offset0:16 offset1:24
	v_add_f64 v[68:69], v[92:93], v[100:101]
	v_add_f64 v[70:71], v[94:95], v[100:101]
	v_add_f64 v[68:69], v[68:69], -v[76:77]
	v_add_f64 v[70:71], v[70:71], -v[78:79]
	ds_write2_b64 v106, v[68:69], v[70:71] offset0:32 offset1:40
	v_add_f64 v[68:69], v[96:97], v[100:101]
	v_add_f64 v[70:71], v[98:99], v[100:101]
	v_add_f64 v[68:69], v[68:69], -v[80:81]
	v_add_f64 v[70:71], v[70:71], -v[82:83]
	ds_write2_b64 v106, v[68:69], v[70:71] offset0:48 offset1:56
	s_waitcnt lgkmcnt(0)
	s_barrier
	ds_read_b128 v[68:71], v105
	ds_read_b128 v[72:75], v105 offset:16
	ds_read_b128 v[76:79], v105 offset:32
	ds_read_b128 v[80:83], v105 offset:48
	s_waitcnt lgkmcnt(3)
	v_add_f64 v[68:69], v[68:69], v[66:67]
	v_add_f64 v[64:65], v[68:69], v[64:65]
	v_add_f64 v[62:63], v[64:65], v[62:63]
	v_add_f64 v[60:61], v[62:63], v[60:61]
	v_mul_f64 v[66:67], v[68:69], s[2:3]
	v_mul_f64 v[68:69], v[64:65], s[2:3]
	v_mul_f64 v[64:65], v[62:63], s[2:3]
	v_mul_f64 v[60:61], v[60:61], s[2:3]
	v_lshlrev_b64 v[62:63], 2, v[42:43]
	v_cvt_f32_f64_e32 v66, v[66:67]
	v_cvt_f32_f64_e32 v67, v[68:69]
	v_cvt_f32_f64_e32 v68, v[64:65]
	v_cvt_f32_f64_e32 v69, v[60:61]
	v_lshl_add_u64 v[42:43], s[4:5], 0, v[62:63]
	global_store_dwordx4 v[42:43], v[66:69], off
	v_add_f64 v[42:43], v[70:71], v[58:59]
	s_or_b32 s4, s0, 1
	v_mul_f64 v[58:59], v[42:43], s[2:3]
	v_add_f64 v[42:43], v[42:43], v[56:57]
	s_ashr_i32 s5, s4, 31
	v_mul_f64 v[56:57], v[42:43], s[2:3]
	v_add_f64 v[42:43], v[42:43], v[54:55]
	s_lshl_b64 s[4:5], s[4:5], 13
	v_mul_f64 v[54:55], v[42:43], s[2:3]
	v_add_f64 v[42:43], v[42:43], v[52:53]
	s_add_u32 s4, s48, s4
	v_mul_f64 v[42:43], v[42:43], s[2:3]
	s_addc_u32 s5, s49, s5
	v_cvt_f32_f64_e32 v58, v[58:59]
	v_cvt_f32_f64_e32 v59, v[56:57]
	v_cvt_f32_f64_e32 v60, v[54:55]
	v_cvt_f32_f64_e32 v61, v[42:43]
	v_lshl_add_u64 v[42:43], s[4:5], 0, v[62:63]
	global_store_dwordx4 v[42:43], v[58:61], off
	s_waitcnt lgkmcnt(2)
	v_add_f64 v[42:43], v[72:73], v[50:51]
	s_or_b32 s4, s0, 2
	v_mul_f64 v[50:51], v[42:43], s[2:3]
	v_add_f64 v[42:43], v[42:43], v[48:49]
	s_ashr_i32 s5, s4, 31
	v_mul_f64 v[48:49], v[42:43], s[2:3]
	v_add_f64 v[42:43], v[42:43], v[46:47]
	s_lshl_b64 s[4:5], s[4:5], 13
	v_mul_f64 v[46:47], v[42:43], s[2:3]
	v_add_f64 v[42:43], v[42:43], v[44:45]
	s_add_u32 s4, s48, s4
	v_mul_f64 v[42:43], v[42:43], s[2:3]
	s_addc_u32 s5, s49, s5
	v_cvt_f32_f64_e32 v50, v[50:51]
	v_cvt_f32_f64_e32 v51, v[48:49]
	v_cvt_f32_f64_e32 v52, v[46:47]
	v_cvt_f32_f64_e32 v53, v[42:43]
	v_lshl_add_u64 v[42:43], s[4:5], 0, v[62:63]
	global_store_dwordx4 v[42:43], v[50:53], off
	v_add_f64 v[42:43], v[74:75], v[40:41]
	s_or_b32 s4, s0, 3
	v_add_f64 v[38:39], v[42:43], v[38:39]
	s_ashr_i32 s5, s4, 31
	v_add_f64 v[36:37], v[38:39], v[36:37]
	s_lshl_b64 s[4:5], s[4:5], 13
	v_add_f64 v[34:35], v[36:37], v[34:35]
	s_add_u32 s4, s48, s4
	v_mul_f64 v[40:41], v[42:43], s[2:3]
	v_mul_f64 v[42:43], v[38:39], s[2:3]
	v_mul_f64 v[38:39], v[36:37], s[2:3]
	v_mul_f64 v[34:35], v[34:35], s[2:3]
	s_addc_u32 s5, s49, s5
	v_cvt_f32_f64_e32 v40, v[40:41]
	v_cvt_f32_f64_e32 v41, v[42:43]
	v_cvt_f32_f64_e32 v42, v[38:39]
	v_cvt_f32_f64_e32 v43, v[34:35]
	v_lshl_add_u64 v[34:35], s[4:5], 0, v[62:63]
	global_store_dwordx4 v[34:35], v[40:43], off
	s_waitcnt lgkmcnt(1)
	v_add_f64 v[34:35], v[76:77], v[32:33]
	s_or_b32 s4, s0, 4
	v_add_f64 v[30:31], v[34:35], v[30:31]
	s_ashr_i32 s5, s4, 31
	v_add_f64 v[28:29], v[30:31], v[28:29]
	s_lshl_b64 s[4:5], s[4:5], 13
	v_add_f64 v[26:27], v[28:29], v[26:27]
	s_add_u32 s4, s48, s4
	v_mul_f64 v[32:33], v[34:35], s[2:3]
	v_mul_f64 v[34:35], v[30:31], s[2:3]
	v_mul_f64 v[30:31], v[28:29], s[2:3]
	v_mul_f64 v[26:27], v[26:27], s[2:3]
	s_addc_u32 s5, s49, s5
	v_cvt_f32_f64_e32 v32, v[32:33]
	v_cvt_f32_f64_e32 v33, v[34:35]
	v_cvt_f32_f64_e32 v34, v[30:31]
	v_cvt_f32_f64_e32 v35, v[26:27]
	v_lshl_add_u64 v[26:27], s[4:5], 0, v[62:63]
	global_store_dwordx4 v[26:27], v[32:35], off
	v_add_f64 v[26:27], v[78:79], v[24:25]
	s_or_b32 s4, s0, 5
	v_add_f64 v[22:23], v[26:27], v[22:23]
	s_ashr_i32 s5, s4, 31
	v_add_f64 v[20:21], v[22:23], v[20:21]
	s_lshl_b64 s[4:5], s[4:5], 13
	v_add_f64 v[18:19], v[20:21], v[18:19]
	s_add_u32 s4, s48, s4
	v_mul_f64 v[24:25], v[26:27], s[2:3]
	v_mul_f64 v[26:27], v[22:23], s[2:3]
	v_mul_f64 v[22:23], v[20:21], s[2:3]
	v_mul_f64 v[18:19], v[18:19], s[2:3]
	s_addc_u32 s5, s49, s5
	v_cvt_f32_f64_e32 v24, v[24:25]
	v_cvt_f32_f64_e32 v25, v[26:27]
	v_cvt_f32_f64_e32 v26, v[22:23]
	v_cvt_f32_f64_e32 v27, v[18:19]
	v_lshl_add_u64 v[18:19], s[4:5], 0, v[62:63]
	global_store_dwordx4 v[18:19], v[24:27], off
	s_waitcnt lgkmcnt(0)
	v_add_f64 v[18:19], v[80:81], v[16:17]
	s_or_b32 s4, s0, 6
	v_add_f64 v[14:15], v[18:19], v[14:15]
	s_ashr_i32 s5, s4, 31
	v_add_f64 v[12:13], v[14:15], v[12:13]
	s_lshl_b64 s[4:5], s[4:5], 13
	v_add_f64 v[10:11], v[12:13], v[10:11]
	s_add_u32 s4, s48, s4
	v_mul_f64 v[16:17], v[18:19], s[2:3]
	v_mul_f64 v[18:19], v[14:15], s[2:3]
	v_mul_f64 v[14:15], v[12:13], s[2:3]
	v_mul_f64 v[10:11], v[10:11], s[2:3]
	s_addc_u32 s5, s49, s5
	v_cvt_f32_f64_e32 v16, v[16:17]
	v_cvt_f32_f64_e32 v17, v[18:19]
	v_cvt_f32_f64_e32 v18, v[14:15]
	v_cvt_f32_f64_e32 v19, v[10:11]
	v_lshl_add_u64 v[10:11], s[4:5], 0, v[62:63]
	global_store_dwordx4 v[10:11], v[16:19], off
	v_add_f64 v[10:11], v[82:83], v[8:9]
	s_or_b32 s0, s0, 7
	v_add_f64 v[6:7], v[10:11], v[6:7]
	s_ashr_i32 s1, s0, 31
	v_add_f64 v[4:5], v[6:7], v[4:5]
	s_lshl_b64 s[0:1], s[0:1], 13
	v_add_f64 v[2:3], v[4:5], v[2:3]
	s_add_u32 s0, s48, s0
	v_mul_f64 v[8:9], v[10:11], s[2:3]
	v_mul_f64 v[10:11], v[6:7], s[2:3]
	v_mul_f64 v[6:7], v[4:5], s[2:3]
	v_mul_f64 v[2:3], v[2:3], s[2:3]
	s_addc_u32 s1, s49, s1
	v_cvt_f32_f64_e32 v8, v[8:9]
	v_cvt_f32_f64_e32 v9, v[10:11]
	v_cvt_f32_f64_e32 v10, v[6:7]
	v_cvt_f32_f64_e32 v11, v[2:3]
	v_lshl_add_u64 v[2:3], s[0:1], 0, v[62:63]
	global_store_dwordx4 v[2:3], v[8:11], off
	s_barrier
